# adds EpiRes<true> (WOUT) epilogue rewrite with streaming f32 base loads + attention K/V staging loads issued together
# speedup vs baseline: 1.0492x; 1.0131x over previous
.LBB0_1439:
	v_and_b32_e32 v128, 63, v180
	v_and_b32_e32 v129, 15, v180
	v_bfe_u32 v130, v180, 4, 2
	v_lshrrev_b32_e32 v131, 6, v180
	v_lshlrev_b32_e32 v131, 12, v131
	v_add_u32_e32 v131, 0x20000, v131
	v_and_b32_e32 v132, 7, v129
	v_xor_b32_e32 v132, v130, v132
	v_lshlrev_b32_e32 v132, 4, v132
	v_lshl_add_u32 v132, v129, 8, v132
	v_add_u32_e32 v169, v131, v132
	v_xor_b32_e32 v170, 64, v169
	v_lshrrev_b32_e32 v133, 2, v128
	v_and_b32_e32 v134, 3, v128
	v_and_b32_e32 v135, 7, v133
	v_lshlrev_b32_e32 v136, 1, v134
	v_xor_b32_e32 v136, v136, v135
	v_lshlrev_b32_e32 v136, 4, v136
	v_lshl_add_u32 v136, v133, 8, v136
	v_add_u32_e32 v171, v131, v136
	v_xor_b32_e32 v172, 16, v171
	s_lshl_b32 s9, s34, 20
	s_cmp_lt_u32 s34, 0x100
	s_cselect_b32 s98, s12, s14
	s_cselect_b32 s99, s13, s15
	s_cselect_b32 s9, s9, 0
	s_add_u32 s98, s98, s9
	s_addc_u32 s99, s99, 0
	v_add_u32_e32 v137, s54, v133
	v_lshlrev_b32_e32 v137, 12, v137
	s_lshl_b32 s9, s8, 8
	s_add_i32 s9, s9, s55
	v_lshl_add_u32 v138, v134, 3, s9
	v_lshl_add_u32 v175, v138, 2, v137
	s_lshl_b32 s9, s34, 8
	s_add_i32 s9, s9, s54
	v_add_u32_e32 v139, s9, v133
	v_lshlrev_b32_e32 v174, 2, v139
	v_lshlrev_b32_e32 v139, 11, v139
	v_lshl_add_u32 v173, v138, 1, v139
	v_cmp_eq_u32_e32 vcc, 0, v134
	global_load_dwordx4 v[188:191], v175, s[98:99]
	global_load_dwordx4 v[192:195], v175, s[98:99] offset:16
	global_load_dwordx4 v[196:199], v175, s[98:99] offset:512
	global_load_dwordx4 v[200:203], v175, s[98:99] offset:528
	s_add_u32 s98, s98, 0x10000
	s_addc_u32 s99, s99, 0
	global_load_dwordx4 v[204:207], v175, s[98:99]
	global_load_dwordx4 v[208:211], v175, s[98:99] offset:16
	global_load_dwordx4 v[212:215], v175, s[98:99] offset:512
	global_load_dwordx4 v[216:219], v175, s[98:99] offset:528
	s_add_u32 s98, s98, 0x10000
	s_addc_u32 s99, s99, 0
	global_load_dwordx4 v[220:223], v175, s[98:99]
	global_load_dwordx4 v[224:227], v175, s[98:99] offset:16
	global_load_dwordx4 v[228:231], v175, s[98:99] offset:512
	global_load_dwordx4 v[232:235], v175, s[98:99] offset:528
	s_add_u32 s98, s98, 0x10000
	s_addc_u32 s99, s99, 0
	global_load_dwordx4 v[236:239], v175, s[98:99]
	global_load_dwordx4 v[240:243], v175, s[98:99] offset:16
	global_load_dwordx4 v[244:247], v175, s[98:99] offset:512
	global_load_dwordx4 v[248:251], v175, s[98:99] offset:528
	s_add_u32 s98, s98, 0x50000
	s_addc_u32 s99, s99, 0
	s_mov_b64 s[8:9], exec
	ds_write_b128 v169, v[124:127]
	ds_write_b128 v170, v[120:123]
	ds_write_b128 v169, v[116:119] offset:128
	ds_write_b128 v170, v[112:115] offset:128
	s_waitcnt lgkmcnt(0)
	ds_read_b128 v[128:131], v171
	ds_read_b128 v[132:135], v172
	ds_read_b128 v[136:139], v171 offset:128
	ds_read_b128 v[140:143], v172 offset:128
	s_waitcnt vmcnt(12)
	s_waitcnt lgkmcnt(0)
	v_pk_add_f32 v[128:129], v[128:129], v[188:189]
	v_pk_add_f32 v[130:131], v[130:131], v[190:191]
	v_pk_add_f32 v[132:133], v[132:133], v[192:193]
	v_pk_add_f32 v[134:135], v[134:135], v[194:195]
	v_pk_mul_f32 v[176:177], v[128:129], v[128:129]
	v_pk_fma_f32 v[176:177], v[130:131], v[130:131], v[176:177]
	v_pk_fma_f32 v[176:177], v[132:133], v[132:133], v[176:177]
	v_pk_fma_f32 v[176:177], v[134:135], v[134:135], v[176:177]
	v_cvt_pk_bf16_f32 v156, v128, v129
	v_cvt_pk_bf16_f32 v157, v130, v131
	v_cvt_pk_bf16_f32 v158, v132, v133
	v_cvt_pk_bf16_f32 v159, v134, v135
	global_store_dwordx4 v173, v[156:159], s[16:17]
	v_pk_add_f32 v[136:137], v[136:137], v[196:197]
	v_pk_add_f32 v[138:139], v[138:139], v[198:199]
	v_pk_add_f32 v[140:141], v[140:141], v[200:201]
	v_pk_add_f32 v[142:143], v[142:143], v[202:203]
	v_pk_fma_f32 v[176:177], v[136:137], v[136:137], v[176:177]
	v_pk_fma_f32 v[176:177], v[138:139], v[138:139], v[176:177]
	v_pk_fma_f32 v[176:177], v[140:141], v[140:141], v[176:177]
	v_pk_fma_f32 v[176:177], v[142:143], v[142:143], v[176:177]
	v_cvt_pk_bf16_f32 v160, v136, v137
	v_cvt_pk_bf16_f32 v161, v138, v139
	v_cvt_pk_bf16_f32 v162, v140, v141
	v_cvt_pk_bf16_f32 v163, v142, v143
	global_store_dwordx4 v173, v[160:163], s[16:17] offset:256
	v_add_f32_e32 v178, v176, v177
	s_nop 1
	v_add_f32_dpp v179, v178, v178 quad_perm:[1,0,3,2] row_mask:0xf bank_mask:0xf
	s_nop 1
	v_add_f32_dpp v181, v179, v179 quad_perm:[2,3,0,1] row_mask:0xf bank_mask:0xf
	s_mov_b64 exec, vcc
	global_atomic_add_f32 v174, v181, s[18:19] offset:0
	s_mov_b64 exec, s[8:9]
	global_load_dwordx4 v[188:191], v175, s[98:99]
	global_load_dwordx4 v[192:195], v175, s[98:99] offset:16
	global_load_dwordx4 v[196:199], v175, s[98:99] offset:512
	global_load_dwordx4 v[200:203], v175, s[98:99] offset:528
	s_add_u32 s98, s98, 0x10000
	s_addc_u32 s99, s99, 0
	v_add_u32_e32 v173, 0x8000, v173
	ds_write_b128 v169, v[108:111]
	ds_write_b128 v170, v[104:107]
	ds_write_b128 v169, v[100:103] offset:128
	ds_write_b128 v170, v[96:99] offset:128
	s_waitcnt lgkmcnt(0)
	ds_read_b128 v[128:131], v171
	ds_read_b128 v[132:135], v172
	ds_read_b128 v[136:139], v171 offset:128
	ds_read_b128 v[140:143], v172 offset:128
	s_waitcnt vmcnt(15)
	s_waitcnt lgkmcnt(0)
	v_pk_add_f32 v[128:129], v[128:129], v[204:205]
	v_pk_add_f32 v[130:131], v[130:131], v[206:207]
	v_pk_add_f32 v[132:133], v[132:133], v[208:209]
	v_pk_add_f32 v[134:135], v[134:135], v[210:211]
	v_pk_mul_f32 v[176:177], v[128:129], v[128:129]
	v_pk_fma_f32 v[176:177], v[130:131], v[130:131], v[176:177]
	v_pk_fma_f32 v[176:177], v[132:133], v[132:133], v[176:177]
	v_pk_fma_f32 v[176:177], v[134:135], v[134:135], v[176:177]
	v_cvt_pk_bf16_f32 v156, v128, v129
	v_cvt_pk_bf16_f32 v157, v130, v131
	v_cvt_pk_bf16_f32 v158, v132, v133
	v_cvt_pk_bf16_f32 v159, v134, v135
	global_store_dwordx4 v173, v[156:159], s[16:17]
	v_pk_add_f32 v[136:137], v[136:137], v[212:213]
	v_pk_add_f32 v[138:139], v[138:139], v[214:215]
	v_pk_add_f32 v[140:141], v[140:141], v[216:217]
	v_pk_add_f32 v[142:143], v[142:143], v[218:219]
	v_pk_fma_f32 v[176:177], v[136:137], v[136:137], v[176:177]
	v_pk_fma_f32 v[176:177], v[138:139], v[138:139], v[176:177]
	v_pk_fma_f32 v[176:177], v[140:141], v[140:141], v[176:177]
	v_pk_fma_f32 v[176:177], v[142:143], v[142:143], v[176:177]
	v_cvt_pk_bf16_f32 v160, v136, v137
	v_cvt_pk_bf16_f32 v161, v138, v139
	v_cvt_pk_bf16_f32 v162, v140, v141
	v_cvt_pk_bf16_f32 v163, v142, v143
	global_store_dwordx4 v173, v[160:163], s[16:17] offset:256
	v_add_f32_e32 v178, v176, v177
	s_nop 1
	v_add_f32_dpp v179, v178, v178 quad_perm:[1,0,3,2] row_mask:0xf bank_mask:0xf
	s_nop 1
	v_add_f32_dpp v181, v179, v179 quad_perm:[2,3,0,1] row_mask:0xf bank_mask:0xf
	s_mov_b64 exec, vcc
	global_atomic_add_f32 v174, v181, s[18:19] offset:64
	s_mov_b64 exec, s[8:9]
	global_load_dwordx4 v[204:207], v175, s[98:99]
	global_load_dwordx4 v[208:211], v175, s[98:99] offset:16
	global_load_dwordx4 v[212:215], v175, s[98:99] offset:512
	global_load_dwordx4 v[216:219], v175, s[98:99] offset:528
	s_add_u32 s98, s98, 0x10000
	s_addc_u32 s99, s99, 0
	v_add_u32_e32 v173, 0x8000, v173
	ds_write_b128 v169, v[92:95]
	ds_write_b128 v170, v[88:91]
	ds_write_b128 v169, v[84:87] offset:128
	ds_write_b128 v170, v[80:83] offset:128
	s_waitcnt lgkmcnt(0)
	ds_read_b128 v[128:131], v171
	ds_read_b128 v[132:135], v172
	ds_read_b128 v[136:139], v171 offset:128
	ds_read_b128 v[140:143], v172 offset:128
	s_waitcnt vmcnt(18)
	s_waitcnt lgkmcnt(0)
	v_pk_add_f32 v[128:129], v[128:129], v[220:221]
	v_pk_add_f32 v[130:131], v[130:131], v[222:223]
	v_pk_add_f32 v[132:133], v[132:133], v[224:225]
	v_pk_add_f32 v[134:135], v[134:135], v[226:227]
	v_pk_mul_f32 v[176:177], v[128:129], v[128:129]
	v_pk_fma_f32 v[176:177], v[130:131], v[130:131], v[176:177]
	v_pk_fma_f32 v[176:177], v[132:133], v[132:133], v[176:177]
	v_pk_fma_f32 v[176:177], v[134:135], v[134:135], v[176:177]
	v_cvt_pk_bf16_f32 v156, v128, v129
	v_cvt_pk_bf16_f32 v157, v130, v131
	v_cvt_pk_bf16_f32 v158, v132, v133
	v_cvt_pk_bf16_f32 v159, v134, v135
	global_store_dwordx4 v173, v[156:159], s[16:17]
	v_pk_add_f32 v[136:137], v[136:137], v[228:229]
	v_pk_add_f32 v[138:139], v[138:139], v[230:231]
	v_pk_add_f32 v[140:141], v[140:141], v[232:233]
	v_pk_add_f32 v[142:143], v[142:143], v[234:235]
	v_pk_fma_f32 v[176:177], v[136:137], v[136:137], v[176:177]
	v_pk_fma_f32 v[176:177], v[138:139], v[138:139], v[176:177]
	v_pk_fma_f32 v[176:177], v[140:141], v[140:141], v[176:177]
	v_pk_fma_f32 v[176:177], v[142:143], v[142:143], v[176:177]
	v_cvt_pk_bf16_f32 v160, v136, v137
	v_cvt_pk_bf16_f32 v161, v138, v139
	v_cvt_pk_bf16_f32 v162, v140, v141
	v_cvt_pk_bf16_f32 v163, v142, v143
	global_store_dwordx4 v173, v[160:163], s[16:17] offset:256
	v_add_f32_e32 v178, v176, v177
	s_nop 1
	v_add_f32_dpp v179, v178, v178 quad_perm:[1,0,3,2] row_mask:0xf bank_mask:0xf
	s_nop 1
	v_add_f32_dpp v181, v179, v179 quad_perm:[2,3,0,1] row_mask:0xf bank_mask:0xf
	s_mov_b64 exec, vcc
	global_atomic_add_f32 v174, v181, s[18:19] offset:128
	s_mov_b64 exec, s[8:9]
	global_load_dwordx4 v[220:223], v175, s[98:99]
	global_load_dwordx4 v[224:227], v175, s[98:99] offset:16
	global_load_dwordx4 v[228:231], v175, s[98:99] offset:512
	global_load_dwordx4 v[232:235], v175, s[98:99] offset:528
	s_add_u32 s98, s98, 0x10000
	s_addc_u32 s99, s99, 0
	v_add_u32_e32 v173, 0x8000, v173
	ds_write_b128 v169, v[76:79]
	ds_write_b128 v170, v[72:75]
	ds_write_b128 v169, v[68:71] offset:128
	ds_write_b128 v170, v[64:67] offset:128
	s_waitcnt lgkmcnt(0)
	ds_read_b128 v[128:131], v171
	ds_read_b128 v[132:135], v172
	ds_read_b128 v[136:139], v171 offset:128
	ds_read_b128 v[140:143], v172 offset:128
	s_waitcnt vmcnt(21)
	s_waitcnt lgkmcnt(0)
	v_pk_add_f32 v[128:129], v[128:129], v[236:237]
	v_pk_add_f32 v[130:131], v[130:131], v[238:239]
	v_pk_add_f32 v[132:133], v[132:133], v[240:241]
	v_pk_add_f32 v[134:135], v[134:135], v[242:243]
	v_pk_mul_f32 v[176:177], v[128:129], v[128:129]
	v_pk_fma_f32 v[176:177], v[130:131], v[130:131], v[176:177]
	v_pk_fma_f32 v[176:177], v[132:133], v[132:133], v[176:177]
	v_pk_fma_f32 v[176:177], v[134:135], v[134:135], v[176:177]
	v_cvt_pk_bf16_f32 v156, v128, v129
	v_cvt_pk_bf16_f32 v157, v130, v131
	v_cvt_pk_bf16_f32 v158, v132, v133
	v_cvt_pk_bf16_f32 v159, v134, v135
	global_store_dwordx4 v173, v[156:159], s[16:17]
	v_pk_add_f32 v[136:137], v[136:137], v[244:245]
	v_pk_add_f32 v[138:139], v[138:139], v[246:247]
	v_pk_add_f32 v[140:141], v[140:141], v[248:249]
	v_pk_add_f32 v[142:143], v[142:143], v[250:251]
	v_pk_fma_f32 v[176:177], v[136:137], v[136:137], v[176:177]
	v_pk_fma_f32 v[176:177], v[138:139], v[138:139], v[176:177]
	v_pk_fma_f32 v[176:177], v[140:141], v[140:141], v[176:177]
	v_pk_fma_f32 v[176:177], v[142:143], v[142:143], v[176:177]
	v_cvt_pk_bf16_f32 v160, v136, v137
	v_cvt_pk_bf16_f32 v161, v138, v139
	v_cvt_pk_bf16_f32 v162, v140, v141
	v_cvt_pk_bf16_f32 v163, v142, v143
	global_store_dwordx4 v173, v[160:163], s[16:17] offset:256
	v_add_f32_e32 v178, v176, v177
	s_nop 1
	v_add_f32_dpp v179, v178, v178 quad_perm:[1,0,3,2] row_mask:0xf bank_mask:0xf
	s_nop 1
	v_add_f32_dpp v181, v179, v179 quad_perm:[2,3,0,1] row_mask:0xf bank_mask:0xf
	s_mov_b64 exec, vcc
	global_atomic_add_f32 v174, v181, s[18:19] offset:192
	s_mov_b64 exec, s[8:9]
	global_load_dwordx4 v[236:239], v175, s[98:99]
	global_load_dwordx4 v[240:243], v175, s[98:99] offset:16
	global_load_dwordx4 v[244:247], v175, s[98:99] offset:512
	global_load_dwordx4 v[248:251], v175, s[98:99] offset:528
	v_add_u32_e32 v173, 0x28000, v173
	ds_write_b128 v169, v[60:63]
	ds_write_b128 v170, v[56:59]
	ds_write_b128 v169, v[52:55] offset:128
	ds_write_b128 v170, v[48:51] offset:128
	s_waitcnt lgkmcnt(0)
	ds_read_b128 v[128:131], v171
	ds_read_b128 v[132:135], v172
	ds_read_b128 v[136:139], v171 offset:128
	ds_read_b128 v[140:143], v172 offset:128
	s_waitcnt vmcnt(21)
	s_waitcnt lgkmcnt(0)
	v_pk_add_f32 v[128:129], v[128:129], v[188:189]
	v_pk_add_f32 v[130:131], v[130:131], v[190:191]
	v_pk_add_f32 v[132:133], v[132:133], v[192:193]
	v_pk_add_f32 v[134:135], v[134:135], v[194:195]
	v_pk_mul_f32 v[176:177], v[128:129], v[128:129]
	v_pk_fma_f32 v[176:177], v[130:131], v[130:131], v[176:177]
	v_pk_fma_f32 v[176:177], v[132:133], v[132:133], v[176:177]
	v_pk_fma_f32 v[176:177], v[134:135], v[134:135], v[176:177]
	v_cvt_pk_bf16_f32 v156, v128, v129
	v_cvt_pk_bf16_f32 v157, v130, v131
	v_cvt_pk_bf16_f32 v158, v132, v133
	v_cvt_pk_bf16_f32 v159, v134, v135
	global_store_dwordx4 v173, v[156:159], s[16:17]
	v_pk_add_f32 v[136:137], v[136:137], v[196:197]
	v_pk_add_f32 v[138:139], v[138:139], v[198:199]
	v_pk_add_f32 v[140:141], v[140:141], v[200:201]
	v_pk_add_f32 v[142:143], v[142:143], v[202:203]
	v_pk_fma_f32 v[176:177], v[136:137], v[136:137], v[176:177]
	v_pk_fma_f32 v[176:177], v[138:139], v[138:139], v[176:177]
	v_pk_fma_f32 v[176:177], v[140:141], v[140:141], v[176:177]
	v_pk_fma_f32 v[176:177], v[142:143], v[142:143], v[176:177]
	v_cvt_pk_bf16_f32 v160, v136, v137
	v_cvt_pk_bf16_f32 v161, v138, v139
	v_cvt_pk_bf16_f32 v162, v140, v141
	v_cvt_pk_bf16_f32 v163, v142, v143
	global_store_dwordx4 v173, v[160:163], s[16:17] offset:256
	v_add_f32_e32 v178, v176, v177
	s_nop 1
	v_add_f32_dpp v179, v178, v178 quad_perm:[1,0,3,2] row_mask:0xf bank_mask:0xf
	s_nop 1
	v_add_f32_dpp v181, v179, v179 quad_perm:[2,3,0,1] row_mask:0xf bank_mask:0xf
	s_mov_b64 exec, vcc
	global_atomic_add_f32 v174, v181, s[18:19] offset:512
	s_mov_b64 exec, s[8:9]
	v_add_u32_e32 v173, 0x8000, v173
	ds_write_b128 v169, v[44:47]
	ds_write_b128 v170, v[40:43]
	ds_write_b128 v169, v[36:39] offset:128
	ds_write_b128 v170, v[32:35] offset:128
	s_waitcnt lgkmcnt(0)
	ds_read_b128 v[128:131], v171
	ds_read_b128 v[132:135], v172
	ds_read_b128 v[136:139], v171 offset:128
	ds_read_b128 v[140:143], v172 offset:128
	s_waitcnt vmcnt(17)
	s_waitcnt lgkmcnt(0)
	v_pk_add_f32 v[128:129], v[128:129], v[204:205]
	v_pk_add_f32 v[130:131], v[130:131], v[206:207]
	v_pk_add_f32 v[132:133], v[132:133], v[208:209]
	v_pk_add_f32 v[134:135], v[134:135], v[210:211]
	v_pk_mul_f32 v[176:177], v[128:129], v[128:129]
	v_pk_fma_f32 v[176:177], v[130:131], v[130:131], v[176:177]
	v_pk_fma_f32 v[176:177], v[132:133], v[132:133], v[176:177]
	v_pk_fma_f32 v[176:177], v[134:135], v[134:135], v[176:177]
	v_cvt_pk_bf16_f32 v156, v128, v129
	v_cvt_pk_bf16_f32 v157, v130, v131
	v_cvt_pk_bf16_f32 v158, v132, v133
	v_cvt_pk_bf16_f32 v159, v134, v135
	global_store_dwordx4 v173, v[156:159], s[16:17]
	v_pk_add_f32 v[136:137], v[136:137], v[212:213]
	v_pk_add_f32 v[138:139], v[138:139], v[214:215]
	v_pk_add_f32 v[140:141], v[140:141], v[216:217]
	v_pk_add_f32 v[142:143], v[142:143], v[218:219]
	v_pk_fma_f32 v[176:177], v[136:137], v[136:137], v[176:177]
	v_pk_fma_f32 v[176:177], v[138:139], v[138:139], v[176:177]
	v_pk_fma_f32 v[176:177], v[140:141], v[140:141], v[176:177]
	v_pk_fma_f32 v[176:177], v[142:143], v[142:143], v[176:177]
	v_cvt_pk_bf16_f32 v160, v136, v137
	v_cvt_pk_bf16_f32 v161, v138, v139
	v_cvt_pk_bf16_f32 v162, v140, v141
	v_cvt_pk_bf16_f32 v163, v142, v143
	global_store_dwordx4 v173, v[160:163], s[16:17] offset:256
	v_add_f32_e32 v178, v176, v177
	s_nop 1
	v_add_f32_dpp v179, v178, v178 quad_perm:[1,0,3,2] row_mask:0xf bank_mask:0xf
	s_nop 1
	v_add_f32_dpp v181, v179, v179 quad_perm:[2,3,0,1] row_mask:0xf bank_mask:0xf
	s_mov_b64 exec, vcc
	global_atomic_add_f32 v174, v181, s[18:19] offset:576
	s_mov_b64 exec, s[8:9]
	v_add_u32_e32 v173, 0x8000, v173
	ds_write_b128 v169, v[28:31]
	ds_write_b128 v170, v[24:27]
	ds_write_b128 v169, v[20:23] offset:128
	ds_write_b128 v170, v[16:19] offset:128
	s_waitcnt lgkmcnt(0)
	ds_read_b128 v[128:131], v171
	ds_read_b128 v[132:135], v172
	ds_read_b128 v[136:139], v171 offset:128
	ds_read_b128 v[140:143], v172 offset:128
	s_waitcnt vmcnt(13)
	s_waitcnt lgkmcnt(0)
	v_pk_add_f32 v[128:129], v[128:129], v[220:221]
	v_pk_add_f32 v[130:131], v[130:131], v[222:223]
	v_pk_add_f32 v[132:133], v[132:133], v[224:225]
	v_pk_add_f32 v[134:135], v[134:135], v[226:227]
	v_pk_mul_f32 v[176:177], v[128:129], v[128:129]
	v_pk_fma_f32 v[176:177], v[130:131], v[130:131], v[176:177]
	v_pk_fma_f32 v[176:177], v[132:133], v[132:133], v[176:177]
	v_pk_fma_f32 v[176:177], v[134:135], v[134:135], v[176:177]
	v_cvt_pk_bf16_f32 v156, v128, v129
	v_cvt_pk_bf16_f32 v157, v130, v131
	v_cvt_pk_bf16_f32 v158, v132, v133
	v_cvt_pk_bf16_f32 v159, v134, v135
	global_store_dwordx4 v173, v[156:159], s[16:17]
	v_pk_add_f32 v[136:137], v[136:137], v[228:229]
	v_pk_add_f32 v[138:139], v[138:139], v[230:231]
	v_pk_add_f32 v[140:141], v[140:141], v[232:233]
	v_pk_add_f32 v[142:143], v[142:143], v[234:235]
	v_pk_fma_f32 v[176:177], v[136:137], v[136:137], v[176:177]
	v_pk_fma_f32 v[176:177], v[138:139], v[138:139], v[176:177]
	v_pk_fma_f32 v[176:177], v[140:141], v[140:141], v[176:177]
	v_pk_fma_f32 v[176:177], v[142:143], v[142:143], v[176:177]
	v_cvt_pk_bf16_f32 v160, v136, v137
	v_cvt_pk_bf16_f32 v161, v138, v139
	v_cvt_pk_bf16_f32 v162, v140, v141
	v_cvt_pk_bf16_f32 v163, v142, v143
	global_store_dwordx4 v173, v[160:163], s[16:17] offset:256
	v_add_f32_e32 v178, v176, v177
	s_nop 1
	v_add_f32_dpp v179, v178, v178 quad_perm:[1,0,3,2] row_mask:0xf bank_mask:0xf
	s_nop 1
	v_add_f32_dpp v181, v179, v179 quad_perm:[2,3,0,1] row_mask:0xf bank_mask:0xf
	s_mov_b64 exec, vcc
	global_atomic_add_f32 v174, v181, s[18:19] offset:640
	s_mov_b64 exec, s[8:9]
	v_add_u32_e32 v173, 0x8000, v173
	ds_write_b128 v169, v[12:15]
	ds_write_b128 v170, v[8:11]
	ds_write_b128 v169, v[4:7] offset:128
	ds_write_b128 v170, v[0:3] offset:128
	s_waitcnt lgkmcnt(0)
	ds_read_b128 v[128:131], v171
	ds_read_b128 v[132:135], v172
	ds_read_b128 v[136:139], v171 offset:128
	ds_read_b128 v[140:143], v172 offset:128
	s_waitcnt vmcnt(9)
	s_waitcnt lgkmcnt(0)
	v_pk_add_f32 v[128:129], v[128:129], v[236:237]
	v_pk_add_f32 v[130:131], v[130:131], v[238:239]
	v_pk_add_f32 v[132:133], v[132:133], v[240:241]
	v_pk_add_f32 v[134:135], v[134:135], v[242:243]
	v_pk_mul_f32 v[176:177], v[128:129], v[128:129]
	v_pk_fma_f32 v[176:177], v[130:131], v[130:131], v[176:177]
	v_pk_fma_f32 v[176:177], v[132:133], v[132:133], v[176:177]
	v_pk_fma_f32 v[176:177], v[134:135], v[134:135], v[176:177]
	v_cvt_pk_bf16_f32 v156, v128, v129
	v_cvt_pk_bf16_f32 v157, v130, v131
	v_cvt_pk_bf16_f32 v158, v132, v133
	v_cvt_pk_bf16_f32 v159, v134, v135
	global_store_dwordx4 v173, v[156:159], s[16:17]
	v_pk_add_f32 v[136:137], v[136:137], v[244:245]
	v_pk_add_f32 v[138:139], v[138:139], v[246:247]
	v_pk_add_f32 v[140:141], v[140:141], v[248:249]
	v_pk_add_f32 v[142:143], v[142:143], v[250:251]
	v_pk_fma_f32 v[176:177], v[136:137], v[136:137], v[176:177]
	v_pk_fma_f32 v[176:177], v[138:139], v[138:139], v[176:177]
	v_pk_fma_f32 v[176:177], v[140:141], v[140:141], v[176:177]
	v_pk_fma_f32 v[176:177], v[142:143], v[142:143], v[176:177]
	v_cvt_pk_bf16_f32 v160, v136, v137
	v_cvt_pk_bf16_f32 v161, v138, v139
	v_cvt_pk_bf16_f32 v162, v140, v141
	v_cvt_pk_bf16_f32 v163, v142, v143
	global_store_dwordx4 v173, v[160:163], s[16:17] offset:256
	v_add_f32_e32 v178, v176, v177
	s_nop 1
	v_add_f32_dpp v179, v178, v178 quad_perm:[1,0,3,2] row_mask:0xf bank_mask:0xf
	s_nop 1
	v_add_f32_dpp v181, v179, v179 quad_perm:[2,3,0,1] row_mask:0xf bank_mask:0xf
	s_mov_b64 exec, vcc
	global_atomic_add_f32 v174, v181, s[18:19] offset:704
	s_mov_b64 exec, s[8:9]

.LBB0_1749:
	v_ashrrev_i32_e32 v16, 3, v7
	v_add_u32_e32 v8, v3, v16
	v_ashrrev_i32_e32 v9, 31, v8
	v_lshlrev_b64 v[8:9], 9, v[8:9]
	v_lshl_add_u64 v[10:11], v[0:1], 0, v[8:9]
	v_lshl_add_u64 v[12:13], v[4:5], 0, v[8:9]
	s_mov_b32 s98, 0x8000
	s_mov_b32 s99, 0
	global_load_dwordx4 v[160:163], v[10:11], off
	global_load_dwordx4 v[164:167], v[12:13], off
	s_cmpk_gt_u32 s28, 0x200
	s_cbranch_scc0 .Latt_ld_done
	v_lshl_add_u64 v[10:11], v[10:11], 0, s[98:99]
	v_lshl_add_u64 v[12:13], v[12:13], 0, s[98:99]
	global_load_dwordx4 v[168:171], v[10:11], off
	global_load_dwordx4 v[172:175], v[12:13], off
	s_cmpk_gt_u32 s28, 0x400
	s_cbranch_scc0 .Latt_ld_done
	v_lshl_add_u64 v[10:11], v[10:11], 0, s[98:99]
	v_lshl_add_u64 v[12:13], v[12:13], 0, s[98:99]
	global_load_dwordx4 v[176:179], v[10:11], off
	global_load_dwordx4 v[184:187], v[12:13], off
.Latt_ld_done:
	v_mad_u64_u32 v[18:19], s[30:31], v16, s45, v[2:3]
	v_lshl_add_u32 v16, v16, 1, v6
	s_waitcnt vmcnt(0)
	ds_write_b128 v18, v[160:163]
	ds_write_b16 v16, v164 offset:27648
	ds_write_b16_d16_hi v16, v164 offset:28048
	ds_write_b16 v16, v165 offset:28448
	ds_write_b16_d16_hi v16, v165 offset:28848
	ds_write_b16 v16, v166 offset:29248
	ds_write_b16_d16_hi v16, v166 offset:29648
	ds_write_b16 v16, v167 offset:30048
	ds_write_b16_d16_hi v16, v167 offset:30448
	s_cmpk_gt_u32 s28, 0x200
	s_cbranch_scc0 .Latt_st_done
	ds_write_b128 v18, v[168:171] offset:9216
	ds_write_b16 v16, v172 offset:27776
	ds_write_b16_d16_hi v16, v172 offset:28176
	ds_write_b16 v16, v173 offset:28576
	ds_write_b16_d16_hi v16, v173 offset:28976
	ds_write_b16 v16, v174 offset:29376
	ds_write_b16_d16_hi v16, v174 offset:29776
	ds_write_b16 v16, v175 offset:30176
	ds_write_b16_d16_hi v16, v175 offset:30576
	s_cmpk_gt_u32 s28, 0x400
	s_cbranch_scc0 .Latt_st_done
	ds_write_b128 v18, v[176:179] offset:18432
	ds_write_b16 v16, v184 offset:27904
	ds_write_b16_d16_hi v16, v184 offset:28304
	ds_write_b16 v16, v185 offset:28704
	ds_write_b16_d16_hi v16, v185 offset:29104
	ds_write_b16 v16, v186 offset:29504
	ds_write_b16_d16_hi v16, v186 offset:29904
	ds_write_b16 v16, v187 offset:30304
	ds_write_b16_d16_hi v16, v187 offset:30704
.Latt_st_done:
.LBB0_1750:
	s_or_b64 exec, exec, s[6:7]
	s_lshl_b32 s6, s14, 6
	s_or_b32 s28, s6, s27
	s_ashr_i32 s14, s66, 4
	s_mov_b64 s[6:7], 0

.LBB0_1766:
	s_or_b64 exec, exec, s[8:9]
	v_or_b32_e32 v10, 16, v12
	v_cmp_gt_u32_e64 s[8:9], s29, v10
	v_add_u32_e32 v10, s28, v10
	v_ashrrev_i32_e32 v11, 31, v10
	v_lshlrev_b64 v[116:117], 11, v[10:11]
	v_lshl_add_u64 v[16:17], v[8:9], 0, v[116:117]
	v_mov_b32_e32 v8, 0
	v_mov_b32_e32 v12, 0
	v_mov_b32_e32 v13, 0
	v_mov_b32_e32 v14, 0
	v_mov_b32_e32 v15, 0
	s_and_saveexec_b64 s[12:13], s[8:9]
	s_cbranch_execz .LBB0_1768
	global_load_dwordx4 v[12:15], v[16:17], off

.LBB0_1770:
	s_or_b64 exec, exec, s[12:13]
	s_load_dwordx2 s[12:13], s[18:19], 0xf0
	s_ashr_i32 s11, s10, 31
	s_lshl_b64 s[10:11], s[10:11], 2
	v_lshl_add_u32 v17, v118, 4, 0
	v_mov_b32_e32 v16, 0
	s_waitcnt lgkmcnt(0)
	s_add_u32 s10, s12, s10
	s_addc_u32 s11, s13, s11
	global_load_dword v125, v113, s[10:11]
	s_cmp_lg_u32 s14, 0
	s_cselect_b64 s[40:41], -1, 0
	s_cmp_eq_u32 s14, 0
	v_mad_u32_u24 v112, v124, s45, v17
	v_mov_b32_e32 v20, 0
	v_mov_b32_e32 v21, 0
	v_mov_b32_e32 v22, 0
	v_mov_b32_e32 v23, 0
	v_mov_b32_e32 v24, 0
	v_mov_b32_e32 v25, 0
	v_mov_b32_e32 v26, 0
	v_mov_b32_e32 v27, 0
	s_barrier
	s_waitcnt vmcnt(1)
	s_cbranch_scc1 .LBB0_1772
	ds_read_b128 v[18:21], v112
	ds_read_b128 v[28:31], v112 offset:64
	s_waitcnt lgkmcnt(1)
	v_mfma_f32_16x16x32_bf16 v[22:25], v[18:21], v[4:7], 0
	s_waitcnt vmcnt(1)
	v_mfma_f32_16x16x32_bf16 v[18:21], v[18:21], v[12:15], 0
	s_waitcnt lgkmcnt(0)
	v_mfma_f32_16x16x32_bf16 v[24:27], v[28:31], v[0:3], v[22:25]
	v_mfma_f32_16x16x32_bf16 v[20:23], v[28:31], v[8:11], v[18:21]
